# phase 0 ends with the XCD grid barrier like every other phase instead of the cooperative-groups grid sync
# speedup vs baseline: 1.0079x; 1.0079x over previous
; DI void xcd_barrier(const XcdBarrier& b) {
;   asm volatile("s_waitcnt vmcnt(0)" ::: "memory");
;   __syncthreads();
;   if (threadIdx.x == 0) {
;     unsigned* bar = b.bar;
;     __builtin_amdgcn_s_waitcnt(0);
;     unsigned nloc = b.st[0], nx = b.st[1];
;     if (nloc == 0u) { xcd_barrier_complete(bar, b.x, nloc, nx); b.st[0] = nloc; b.st[1] = nx; }
; __global__ void __launch_bounds__(NTH) fwd_megakernel(Params p) {
;     ...
;   for (int ph = p.ph_lo; ph < p.ph_hi; ++ph) {
;     if (ph >= PH_PRE && (((ph - PH_PRE) / PH_PER_LAYER) & 1) == 1 && (ph - PH_PRE) % PH_PER_LAYER == 3) continue;
;     run_phase(p, ph);
;     if (ph + 1 < p.ph_hi) { if (ph == 0) grid.sync(); else xcd_barrier(xb); }
.LBB0_2667:
	s_add_i32 s16, s78, 1
	s_cmp_ge_i32 s16, s79
	s_cbranch_scc1 .LBB0_2681
	v_readlane_b32 s0, v253, 46
	v_readlane_b32 s1, v253, 47
	s_and_b64 vcc, exec, s[0:1]
	s_nop 0
	s_waitcnt vmcnt(0)
	s_waitcnt lgkmcnt(0)
	s_barrier
	s_mov_b64 s[0:1], exec
	v_readlane_b32 s2, v250, 5
	v_readlane_b32 s3, v250, 6
	s_and_b64 s[2:3], s[0:1], s[2:3]
	s_mov_b64 exec, s[2:3]
	s_cbranch_execz .LBB0_2723
	v_readlane_b32 s2, v253, 8
	s_waitcnt vmcnt(0) expcnt(0) lgkmcnt(0)
	s_nop 0
	v_mov_b32_e32 v0, s2
	ds_read_b32 v3, v0
	v_readlane_b32 s2, v253, 9
	s_waitcnt lgkmcnt(0)
	v_cmp_ne_u32_e32 vcc, 0, v3
	v_mov_b32_e32 v0, s2
	ds_read_b32 v2, v0
	s_cbranch_vccnz .LBB0_2687
	s_mov_b32 s8, 1
	s_branch .LBB0_2673
